# census evaluated once (first class barrier), flags kept in spare spill lanes: later barriers start with the arrive instead of a census load
# baseline (speedup 1.0000x reference)
; #define LAS __attribute__((address_space(3)))
; __device__ __forceinline__ unsigned xb_ld(unsigned* p)              { return __hip_atomic_load(p, __ATOMIC_RELAXED, __HIP_MEMORY_SCOPE_AGENT); }
; __device__ __forceinline__ unsigned xb_add(unsigned* p, unsigned v) { return __hip_atomic_fetch_add(p, v, __ATOMIC_RELAXED, __HIP_MEMORY_SCOPE_AGENT); }
; __device__ __forceinline__ unsigned xb_xcc_id() { return (unsigned)__builtin_amdgcn_s_getreg((3 << 11) | 20) & 0xFu; }
; #define XB_SPIN(cond, bar) do { unsigned _sp = 0; while (cond) { __builtin_amdgcn_s_sleep(1); \
;     if ((++_sp & 255u) == 0u) { if (xb_ld(&(bar)[XB_TMO])) break; if (_sp > XB_SPIN_CAP) { atomicAdd(&(bar)[XB_TMO], 1u); break; } } } } while (0)
; __device__ __forceinline__ XcdBarrier xcd_barrier_post(unsigned* bar, volatile LAS unsigned* st) {
;     XcdBarrier b; b.bar = bar; b.x = xb_xcc_id(); b.st = st;
;     if (threadIdx.x == 0) (void)xb_add(&bar[XB_XCNT(b.x)], 1u);
;     return b;
; }
; __device__ __forceinline__ void xcd_barrier(const XcdBarrier& b) {
;     asm volatile("s_waitcnt vmcnt(0)" ::: "memory");
;     __syncthreads();
;     if (threadIdx.x == 0) {
;         unsigned* bar = b.bar;
;         __builtin_amdgcn_s_waitcnt(0);
;         unsigned nloc = b.st[0], nx = b.st[1];
;         if (nloc == 0u) { xcd_barrier_complete(bar, b.x, nloc, nx); b.st[0] = nloc; b.st[1] = nx; }
;         const unsigned old = xb_add(&bar[XB_XSUB(b.x)], 1u);
;         const unsigned gen = old / nloc;
;         if (old + 1u == (gen + 1u) * nloc) {
;             __builtin_amdgcn_fence(__ATOMIC_RELEASE, "agent");
;             asm volatile("s_waitcnt vmcnt(0)" ::: "memory");
;             const unsigned og = xb_add(&bar[XB_TOP], 1u);
;             const unsigned tg = og / nx;
;             if (og + 1u == (tg + 1u) * nx) xb_add(&bar[XB_TOPGEN], 1u);
;             else XB_SPIN(xb_ld(&bar[XB_TOPGEN]) == tg, bar);
;             __builtin_amdgcn_fence(__ATOMIC_ACQUIRE, "agent");
;             xb_add(&bar[XB_XGEN(b.x)], 1u);
;             asm volatile("s_waitcnt vmcnt(0)" ::: "memory");
;         } else {
;             XB_SPIN(xb_ld(&bar[XB_XGEN(b.x)]) == gen, bar);
;             __builtin_amdgcn_fence(__ATOMIC_ACQUIRE, "agent");
;             asm volatile("s_waitcnt vmcnt(0)" ::: "memory");
;         }
;     }
;     __syncthreads();
; }
.LBB0_322:
	s_waitcnt vmcnt(0)
	s_waitcnt vmcnt(0) lgkmcnt(0)
	s_barrier
	s_mov_b64 s[0:1], exec
	v_readlane_b32 s2, v247, 37
	v_readlane_b32 s3, v247, 38
	s_and_b64 s[2:3], s[0:1], s[2:3]
	s_mov_b64 exec, s[2:3]
	s_cbranch_execz .LBB0_374
	v_readlane_b32 s5, v247, 36
	s_and_b32 s2, s90, 31
	s_lshl_b32 s2, s2, 6
	s_add_u32 s6, s62, s2
	s_addc_u32 s7, s63, 0
	s_add_u32 s6, s6, 0xa000
	s_addc_u32 s7, s7, 0
	v_mov_b32_e32 v1, 0
	global_load_dword v3, v1, s[6:7] sc1
	s_and_b32 s2, s90, 7
	s_lshl_b32 s2, s2, 7
	s_lshr_b32 s6, s5, 2
	s_and_b32 s6, s6, 1
	s_lshl_b32 s6, s6, 6
	s_add_i32 s2, s2, s6
	s_add_u32 s6, s62, s2
	s_addc_u32 s7, s63, 0
	s_add_u32 s6, s6, 0xa800
	s_addc_u32 s7, s7, 0
	global_load_dword v2, v1, s[6:7] sc1
	s_and_b32 s6, s5, 7
	s_lshl_b32 s6, s6, 2
	s_lshl_b32 s6, 8, s6
	s_and_b32 s7, s5, 3
	s_lshl_b32 s7, s7, 3
	s_lshl_b32 s7, 32, s7
	s_mov_b32 s4, 0
	s_waitcnt vmcnt(0) lgkmcnt(0)
	v_cmp_eq_u32_e32 vcc, s6, v3
	s_cmp_lg_u64 vcc, 0
	s_cselect_b32 s6, 1, 0
	v_cmp_eq_u32_e32 vcc, s7, v2
	s_cmp_lg_u64 vcc, 0
	s_cselect_b32 s5, 1, 0
	v_writelane_b32 v246, s6, 62
	v_writelane_b32 v246, s5, 63
	v_mov_b32_e32 v2, 1
	s_and_b32 s2, s90, 7
	s_lshl_b32 s2, s2, 7
	s_add_u32 s2, s62, s2
	s_addc_u32 s3, s63, 0
	s_add_u32 s2, s2, 0xe000
	s_addc_u32 s3, s3, 0
	s_add_u32 s6, s62, 0xd000
	s_addc_u32 s7, s63, 0
	s_cmp_eq_u32 s5, 1
	s_cbranch_scc1 .Lgrpbar3_same
	buffer_wbl2 sc1
	s_waitcnt vmcnt(0)
.Lgrpbar3_same:
	buffer_inv sc1
	global_atomic_add v1, v2, s[2:3]
	global_atomic_add v1, v2, s[6:7]
.Lgrpbar3_spin:
	global_load_dword v3, v1, s[2:3] sc1
	s_waitcnt vmcnt(0)
	v_cmp_lt_u32_e32 vcc, 31, v3
	s_cbranch_vccnz .Lgrpbar3_done
	s_sleep 1
	s_add_i32 s4, s4, 1
	s_cmp_lt_u32 s4, 0x200000
	s_cbranch_scc1 .Lgrpbar3_spin

; __device__ __forceinline__ unsigned xb_ld(unsigned* p)              { return __hip_atomic_load(p, __ATOMIC_RELAXED, __HIP_MEMORY_SCOPE_AGENT); }
; __device__ __forceinline__ unsigned xb_add(unsigned* p, unsigned v) { return __hip_atomic_fetch_add(p, v, __ATOMIC_RELAXED, __HIP_MEMORY_SCOPE_AGENT); }
; #define XB_SPIN(cond, bar) do { unsigned _sp = 0; while (cond) { __builtin_amdgcn_s_sleep(1); \
;     if ((++_sp & 255u) == 0u) { if (xb_ld(&(bar)[XB_TMO])) break; if (_sp > XB_SPIN_CAP) { atomicAdd(&(bar)[XB_TMO], 1u); break; } } } } while (0)
; __device__ __forceinline__ void xcd_barrier(const XcdBarrier& b) {
;     asm volatile("s_waitcnt vmcnt(0)" ::: "memory");
;     __syncthreads();
;     if (threadIdx.x == 0) {
;         unsigned* bar = b.bar;
;         __builtin_amdgcn_s_waitcnt(0);
;         unsigned nloc = b.st[0], nx = b.st[1];
;         if (nloc == 0u) { xcd_barrier_complete(bar, b.x, nloc, nx); b.st[0] = nloc; b.st[1] = nx; }
;         const unsigned old = xb_add(&bar[XB_XSUB(b.x)], 1u);
;         const unsigned gen = old / nloc;
;         if (old + 1u == (gen + 1u) * nloc) {
;             __builtin_amdgcn_fence(__ATOMIC_RELEASE, "agent");
;             asm volatile("s_waitcnt vmcnt(0)" ::: "memory");
;             const unsigned og = xb_add(&bar[XB_TOP], 1u);
;             const unsigned tg = og / nx;
;             if (og + 1u == (tg + 1u) * nx) xb_add(&bar[XB_TOPGEN], 1u);
;             else XB_SPIN(xb_ld(&bar[XB_TOPGEN]) == tg, bar);
;             __builtin_amdgcn_fence(__ATOMIC_ACQUIRE, "agent");
;             xb_add(&bar[XB_XGEN(b.x)], 1u);
;             asm volatile("s_waitcnt vmcnt(0)" ::: "memory");
;         } else {
;             XB_SPIN(xb_ld(&bar[XB_XGEN(b.x)]) == gen, bar);
;             __builtin_amdgcn_fence(__ATOMIC_ACQUIRE, "agent");
;             asm volatile("s_waitcnt vmcnt(0)" ::: "memory");
;         }
;     }
;     __syncthreads();
; }
.LBB0_507:
	v_readlane_b32 s18, v247, 47
	v_readlane_b32 s19, v247, 48
	s_cmp_gt_i32 s19, 4
	s_cbranch_scc0 .LBB0_561
	s_waitcnt vmcnt(0)
	s_waitcnt vmcnt(0) lgkmcnt(0)
	s_barrier
	s_mov_b64 s[0:1], exec
	v_readlane_b32 s2, v247, 37
	v_readlane_b32 s3, v247, 38
	s_and_b64 s[2:3], s[0:1], s[2:3]
	s_mov_b64 exec, s[2:3]
	s_cbranch_execz .LBB0_560
	v_readlane_b32 s5, v246, 63
	s_and_b32 s2, s90, 7
	s_lshl_b32 s2, s2, 7
	s_add_u32 s2, s62, s2
	s_addc_u32 s3, s63, 0
	s_add_u32 s2, s2, 0xf000
	s_addc_u32 s3, s3, 0
	s_add_u32 s6, s62, 0xd000
	s_addc_u32 s7, s63, 0
	v_mov_b32_e32 v1, 0
	v_mov_b32_e32 v2, 1
	s_mov_b32 s4, 0
	s_waitcnt vmcnt(0) lgkmcnt(0)
	s_cmp_eq_u32 s5, 1
	s_cbranch_scc1 .Lgrpbar4_same
	buffer_wbl2 sc1
	s_waitcnt vmcnt(0)

; __device__ __forceinline__ unsigned xb_ld(unsigned* p)              { return __hip_atomic_load(p, __ATOMIC_RELAXED, __HIP_MEMORY_SCOPE_AGENT); }
; __device__ __forceinline__ unsigned xb_add(unsigned* p, unsigned v) { return __hip_atomic_fetch_add(p, v, __ATOMIC_RELAXED, __HIP_MEMORY_SCOPE_AGENT); }
; #define XB_SPIN(cond, bar) do { unsigned _sp = 0; while (cond) { __builtin_amdgcn_s_sleep(1); \
;     if ((++_sp & 255u) == 0u) { if (xb_ld(&(bar)[XB_TMO])) break; if (_sp > XB_SPIN_CAP) { atomicAdd(&(bar)[XB_TMO], 1u); break; } } } } while (0)
; __device__ __forceinline__ void xcd_barrier(const XcdBarrier& b) {
;     asm volatile("s_waitcnt vmcnt(0)" ::: "memory");
;     __syncthreads();
;     if (threadIdx.x == 0) {
;         unsigned* bar = b.bar;
;         __builtin_amdgcn_s_waitcnt(0);
;         unsigned nloc = b.st[0], nx = b.st[1];
;         if (nloc == 0u) { xcd_barrier_complete(bar, b.x, nloc, nx); b.st[0] = nloc; b.st[1] = nx; }
;         const unsigned old = xb_add(&bar[XB_XSUB(b.x)], 1u);
;         const unsigned gen = old / nloc;
;         if (old + 1u == (gen + 1u) * nloc) {
;             __builtin_amdgcn_fence(__ATOMIC_RELEASE, "agent");
;             asm volatile("s_waitcnt vmcnt(0)" ::: "memory");
;             const unsigned og = xb_add(&bar[XB_TOP], 1u);
;             const unsigned tg = og / nx;
;             if (og + 1u == (tg + 1u) * nx) xb_add(&bar[XB_TOPGEN], 1u);
;             else XB_SPIN(xb_ld(&bar[XB_TOPGEN]) == tg, bar);
;             __builtin_amdgcn_fence(__ATOMIC_ACQUIRE, "agent");
;             xb_add(&bar[XB_XGEN(b.x)], 1u);
;             asm volatile("s_waitcnt vmcnt(0)" ::: "memory");
;         } else {
;             XB_SPIN(xb_ld(&bar[XB_XGEN(b.x)]) == gen, bar);
;             __builtin_amdgcn_fence(__ATOMIC_ACQUIRE, "agent");
;             asm volatile("s_waitcnt vmcnt(0)" ::: "memory");
;         }
;     }
;     __syncthreads();
; }
.LBB0_729:
	s_waitcnt vmcnt(0)
	s_waitcnt vmcnt(0) lgkmcnt(0)
	s_barrier
	s_mov_b64 s[0:1], exec
	v_readlane_b32 s2, v247, 37
	v_readlane_b32 s3, v247, 38
	s_and_b64 s[2:3], s[0:1], s[2:3]
	s_mov_b64 exec, s[2:3]
	s_cbranch_execz .LBB0_781
	v_readlane_b32 s5, v246, 62
	s_and_b32 s2, s90, 31
	s_lshl_b32 s2, s2, 6
	s_add_u32 s2, s62, s2
	s_addc_u32 s3, s63, 0
	s_add_u32 s2, s2, 0xb000
	s_addc_u32 s3, s3, 0
	s_add_u32 s6, s62, 0xc000
	s_addc_u32 s7, s63, 0
	v_mov_b32_e32 v1, 0
	v_mov_b32_e32 v2, 1
	s_mov_b32 s4, 0
	s_waitcnt vmcnt(0) lgkmcnt(0)
	s_cmp_eq_u32 s5, 1
	s_cbranch_scc1 .Lgrpbar2_same
	buffer_wbl2 sc1
	s_waitcnt vmcnt(0)

; __device__ __forceinline__ unsigned xb_ld(unsigned* p)              { return __hip_atomic_load(p, __ATOMIC_RELAXED, __HIP_MEMORY_SCOPE_AGENT); }
; __device__ __forceinline__ unsigned xb_add(unsigned* p, unsigned v) { return __hip_atomic_fetch_add(p, v, __ATOMIC_RELAXED, __HIP_MEMORY_SCOPE_AGENT); }
; #define XB_SPIN(cond, bar) do { unsigned _sp = 0; while (cond) { __builtin_amdgcn_s_sleep(1); \
;     if ((++_sp & 255u) == 0u) { if (xb_ld(&(bar)[XB_TMO])) break; if (_sp > XB_SPIN_CAP) { atomicAdd(&(bar)[XB_TMO], 1u); break; } } } } while (0)
; __device__ __forceinline__ void xcd_barrier(const XcdBarrier& b) {
;     asm volatile("s_waitcnt vmcnt(0)" ::: "memory");
;     __syncthreads();
;     if (threadIdx.x == 0) {
;         unsigned* bar = b.bar;
;         __builtin_amdgcn_s_waitcnt(0);
;         unsigned nloc = b.st[0], nx = b.st[1];
;         if (nloc == 0u) { xcd_barrier_complete(bar, b.x, nloc, nx); b.st[0] = nloc; b.st[1] = nx; }
;         const unsigned old = xb_add(&bar[XB_XSUB(b.x)], 1u);
;         const unsigned gen = old / nloc;
;         if (old + 1u == (gen + 1u) * nloc) {
;             __builtin_amdgcn_fence(__ATOMIC_RELEASE, "agent");
;             asm volatile("s_waitcnt vmcnt(0)" ::: "memory");
;             const unsigned og = xb_add(&bar[XB_TOP], 1u);
;             const unsigned tg = og / nx;
;             if (og + 1u == (tg + 1u) * nx) xb_add(&bar[XB_TOPGEN], 1u);
;             else XB_SPIN(xb_ld(&bar[XB_TOPGEN]) == tg, bar);
;             __builtin_amdgcn_fence(__ATOMIC_ACQUIRE, "agent");
;             xb_add(&bar[XB_XGEN(b.x)], 1u);
;             asm volatile("s_waitcnt vmcnt(0)" ::: "memory");
;         } else {
;             XB_SPIN(xb_ld(&bar[XB_XGEN(b.x)]) == gen, bar);
;             __builtin_amdgcn_fence(__ATOMIC_ACQUIRE, "agent");
;             asm volatile("s_waitcnt vmcnt(0)" ::: "memory");
;         }
;     }
;     __syncthreads();
; }
.LBB0_823:
	s_cmp_lt_i32 s19, 7
	s_cbranch_scc1 .LBB0_877
	s_waitcnt vmcnt(0)
	s_waitcnt vmcnt(0) lgkmcnt(0)
	s_barrier
	s_mov_b64 s[0:1], exec
	v_readlane_b32 s2, v247, 37
	v_readlane_b32 s3, v247, 38
	s_and_b64 s[2:3], s[0:1], s[2:3]
	s_mov_b64 exec, s[2:3]
	s_cbranch_execz .LBB0_876
	v_readlane_b32 s5, v246, 62
	s_and_b32 s2, s90, 31
	s_lshl_b32 s2, s2, 6
	s_add_u32 s2, s62, s2
	s_addc_u32 s3, s63, 0
	s_add_u32 s2, s2, 0x8000
	s_addc_u32 s3, s3, 0
	s_add_u32 s6, s62, 0xc000
	s_addc_u32 s7, s63, 0
	v_mov_b32_e32 v1, 0
	v_mov_b32_e32 v2, 1
	s_mov_b32 s4, 0
	s_waitcnt vmcnt(0) lgkmcnt(0)
	s_cmp_eq_u32 s5, 1
	s_cbranch_scc1 .Lgrpbar1_same
	buffer_wbl2 sc1
	s_waitcnt vmcnt(0)

; __device__ __forceinline__ unsigned xb_ld(unsigned* p)              { return __hip_atomic_load(p, __ATOMIC_RELAXED, __HIP_MEMORY_SCOPE_AGENT); }
; __device__ __forceinline__ unsigned xb_add(unsigned* p, unsigned v) { return __hip_atomic_fetch_add(p, v, __ATOMIC_RELAXED, __HIP_MEMORY_SCOPE_AGENT); }
; #define XB_SPIN(cond, bar) do { unsigned _sp = 0; while (cond) { __builtin_amdgcn_s_sleep(1); \
;     if ((++_sp & 255u) == 0u) { if (xb_ld(&(bar)[XB_TMO])) break; if (_sp > XB_SPIN_CAP) { atomicAdd(&(bar)[XB_TMO], 1u); break; } } } } while (0)
; __device__ __forceinline__ void xcd_barrier(const XcdBarrier& b) {
;     asm volatile("s_waitcnt vmcnt(0)" ::: "memory");
;     __syncthreads();
;     if (threadIdx.x == 0) {
;         unsigned* bar = b.bar;
;         __builtin_amdgcn_s_waitcnt(0);
;         unsigned nloc = b.st[0], nx = b.st[1];
;         if (nloc == 0u) { xcd_barrier_complete(bar, b.x, nloc, nx); b.st[0] = nloc; b.st[1] = nx; }
;         const unsigned old = xb_add(&bar[XB_XSUB(b.x)], 1u);
;         const unsigned gen = old / nloc;
;         if (old + 1u == (gen + 1u) * nloc) {
;             __builtin_amdgcn_fence(__ATOMIC_RELEASE, "agent");
;             asm volatile("s_waitcnt vmcnt(0)" ::: "memory");
;             const unsigned og = xb_add(&bar[XB_TOP], 1u);
;             const unsigned tg = og / nx;
;             if (og + 1u == (tg + 1u) * nx) xb_add(&bar[XB_TOPGEN], 1u);
;             else XB_SPIN(xb_ld(&bar[XB_TOPGEN]) == tg, bar);
;             __builtin_amdgcn_fence(__ATOMIC_ACQUIRE, "agent");
;             xb_add(&bar[XB_XGEN(b.x)], 1u);
;             asm volatile("s_waitcnt vmcnt(0)" ::: "memory");
;         } else {
;             XB_SPIN(xb_ld(&bar[XB_XGEN(b.x)]) == gen, bar);
;             __builtin_amdgcn_fence(__ATOMIC_ACQUIRE, "agent");
;             asm volatile("s_waitcnt vmcnt(0)" ::: "memory");
;         }
;     }
;     __syncthreads();
; }
.LBB0_902:
	s_cmp_lt_i32 s19, 9
	s_cbranch_scc1 .LBB0_956
	s_waitcnt vmcnt(0)
	s_waitcnt vmcnt(0) lgkmcnt(0)
	s_barrier
	s_mov_b64 s[0:1], exec
	v_readlane_b32 s2, v247, 37
	v_readlane_b32 s3, v247, 38
	s_and_b64 s[2:3], s[0:1], s[2:3]
	s_mov_b64 exec, s[2:3]
	s_cbranch_execz .LBB0_955
	v_readlane_b32 s5, v246, 62
	s_and_b32 s2, s90, 31
	s_lshl_b32 s2, s2, 6
	s_add_u32 s2, s62, s2
	s_addc_u32 s3, s63, 0
	s_add_u32 s2, s2, 0x9000
	s_addc_u32 s3, s3, 0
	s_add_u32 s6, s62, 0xc000
	s_addc_u32 s7, s63, 0
	v_mov_b32_e32 v1, 0
	v_mov_b32_e32 v2, 1
	s_mov_b32 s4, 0
	s_waitcnt vmcnt(0) lgkmcnt(0)
	s_cmp_eq_u32 s5, 1
	s_cbranch_scc1 .Lgrpbar0_same
	buffer_wbl2 sc1
	s_waitcnt vmcnt(0)
